# hot GEMM K-loops: back-to-back s_setprio 0/1 toggles and the already-satisfied second lgkmcnt(0) removed (16 issue slots per 2 K-tiles)
# speedup vs baseline: 1.0390x; 1.0390x over previous
; #define PG8_STAGE(bufoff, gbase, voff) do { _Pragma("unroll") for (int _i = 0; _i < 2; ++_i) \
;         __builtin_amdgcn_global_load_lds((const unsigned*)((const char*)(gbase) + (voff)[_i]), (PG8_LAS unsigned*)(lds + (bufoff) + ldsw + _i * 8192), 16, 0, 0); } while (0)
; #define PG8_LDA(dst, b, h) do { _Pragma("unroll") for (int m = 0; m < 4; ++m) _Pragma("unroll") for (int k = 0; k < 2; ++k) dst[m][k] = *(const PG8_LAS bf16x8*)(lds + PG8_SA(b, h) + aoff + m * 2048 + k * 1024); } while (0)
; #define PG8_LDB(dst, b, h) do { _Pragma("unroll") for (int n = 0; n < 2; ++n) _Pragma("unroll") for (int k = 0; k < 2; ++k) dst[n][k] = *(const PG8_LAS bf16x8*)(lds + PG8_SB(b, h) + boff + n * 2048 + k * 1024); } while (0)
; #define PG8_WAIT_V(n) asm volatile("s_waitcnt vmcnt(" #n ")" ::: "memory")
; #define PG8_WAIT_L(n) asm volatile("s_waitcnt lgkmcnt(" #n ")" ::: "memory")
; #define PG8_BAR __builtin_amdgcn_s_barrier()
; #define PG8_SCHED __builtin_amdgcn_sched_barrier(0)
; template <class Epi, class Sched, bool ALIGN_EPI = false, bool SP2 = false>
; __device__ __forceinline__ void gemm_phase(PG8_LAS unsigned char* lds, const Gemm g, const Sched& S, const Epi& E, const int wave0) {
;     ...
;         const char* nA = has_next ? (const char*)g.A + (size_t)nxt.pm * tstep : cA; const char* nB = has_next ? (const char*)g.Bt + (size_t)nxt.pn * tstep : cB;
;         for (int t = 0; t < nt; t += 2) {
;             const bool last = (t == nt - 2);
;             const char* a1 = cA + (size_t)(t + 1) * kstep;
;             const char* a2 = last ? nA : cA + (size_t)(t + 2) * kstep; const char* b2 = last ? nB : cB + (size_t)(t + 2) * kstep;
;             const char* a3 = a2 + kstep; const char* b3 = b2 + kstep;
;             if (last && has_next) S.a_ready(nxt);
;             if constexpr (SP2) {
;             PG8_LDB(B0, 0, 0); PG8_LDB(B1, 0, 1); PG8_SCHED; PG8_LDA(At, 0, 0); PG8_STAGE(PG8_SA(1, 1), a1 + hstep, voffA);
;             PG8_WAIT_V(8); PG8_WAIT_L(0); PG8_BAR; PG8_MMA(0, 0, At, B0); PG8_MMA(0, 1, At, B1); PG8_BAR; PG8_SCHED;
;             PG8_LDA(At, 0, 1); PG8_STAGE(PG8_SB(0, 0), b2, voffB); PG8_STAGE(PG8_SB(0, 1), b2 + hstep, voffB); PG8_STAGE(PG8_SA(0, 0), a2, voffA);
;             PG8_WAIT_V(8); PG8_WAIT_L(0); PG8_BAR; PG8_MMA(1, 0, At, B0); PG8_MMA(1, 1, At, B1); PG8_BAR; PG8_SCHED;
.LBB0_1024:
	s_add_u32 s8, s10, 0x100
	s_addc_u32 s9, s11, 0
	s_add_i32 s18, 0, 0x10000
	s_cmp_eq_u32 s59, 40
	s_cselect_b32 s51, s45, s9
	s_cselect_b32 s50, s44, s8
	s_cselect_b32 s49, s47, s58
	s_cselect_b32 s48, s46, s57
	s_add_i32 s19, 0, 0x14000
	v_add_u32_e32 v140, s18, v247
	v_add_u32_e32 v156, s19, v247
	ds_read_b128 v[64:67], v140
	ds_read_b128 v[68:71], v140 offset:1024
	ds_read_b128 v[136:139], v140 offset:2048
	ds_read_b128 v[140:143], v140 offset:3072
	ds_read_b128 v[144:147], v156
	ds_read_b128 v[148:151], v156 offset:1024
	ds_read_b128 v[152:155], v156 offset:2048
	ds_read_b128 v[156:159], v156 offset:3072
	s_add_i32 m0, s33, 0xc000
	ds_read_b128 v[160:163], v245
	ds_read_b128 v[164:167], v245 offset:1024
	ds_read_b128 v[168:171], v245 offset:2048
	ds_read_b128 v[172:175], v245 offset:3072
	ds_read_b128 v[176:179], v245 offset:4096
	ds_read_b128 v[180:183], v245 offset:5120
	ds_read_b128 v[184:187], v245 offset:6144
	ds_read_b128 v[188:191], v245 offset:7168
	global_load_lds_dwordx4 v224, s[10:11]
	s_add_i32 m0, s33, 0xe000
	s_nop 0
	global_load_lds_dwordx4 v226, s[10:11]
	s_waitcnt vmcnt(8)
	s_waitcnt lgkmcnt(0)
	s_barrier
	s_setprio 1
	v_mfma_f32_16x16x32_bf16 v[132:135], v[64:67], v[160:163], v[132:135]
	v_mfma_f32_16x16x32_bf16 v[128:131], v[136:139], v[160:163], v[128:131]
	v_mfma_f32_16x16x32_bf16 v[116:119], v[64:67], v[168:171], v[116:119]
	v_mfma_f32_16x16x32_bf16 v[108:111], v[136:139], v[168:171], v[108:111]
	v_mfma_f32_16x16x32_bf16 v[100:103], v[64:67], v[176:179], v[100:103]
	v_mfma_f32_16x16x32_bf16 v[92:95], v[136:139], v[176:179], v[92:95]
	v_mfma_f32_16x16x32_bf16 v[84:87], v[64:67], v[184:187], v[84:87]
	v_mfma_f32_16x16x32_bf16 v[76:79], v[136:139], v[184:187], v[76:79]
	v_mfma_f32_16x16x32_bf16 v[132:135], v[68:71], v[164:167], v[132:135]
	v_mfma_f32_16x16x32_bf16 v[128:131], v[140:143], v[164:167], v[128:131]
	v_mfma_f32_16x16x32_bf16 v[116:119], v[68:71], v[172:175], v[116:119]
	v_mfma_f32_16x16x32_bf16 v[108:111], v[140:143], v[172:175], v[108:111]
	v_mfma_f32_16x16x32_bf16 v[100:103], v[68:71], v[180:183], v[100:103]
	v_mfma_f32_16x16x32_bf16 v[92:95], v[140:143], v[180:183], v[92:95]
	v_mfma_f32_16x16x32_bf16 v[84:87], v[68:71], v[188:191], v[84:87]
	v_mfma_f32_16x16x32_bf16 v[76:79], v[140:143], v[188:191], v[76:79]
	v_mfma_f32_16x16x32_bf16 v[124:127], v[144:147], v[160:163], v[124:127]
	v_mfma_f32_16x16x32_bf16 v[120:123], v[152:155], v[160:163], v[120:123]
	v_mfma_f32_16x16x32_bf16 v[112:115], v[144:147], v[168:171], v[112:115]
	v_mfma_f32_16x16x32_bf16 v[104:107], v[152:155], v[168:171], v[104:107]
	v_mfma_f32_16x16x32_bf16 v[96:99], v[144:147], v[176:179], v[96:99]
	v_mfma_f32_16x16x32_bf16 v[88:91], v[152:155], v[176:179], v[88:91]
	v_mfma_f32_16x16x32_bf16 v[80:83], v[144:147], v[184:187], v[80:83]
	v_mfma_f32_16x16x32_bf16 v[72:75], v[152:155], v[184:187], v[72:75]
	v_mfma_f32_16x16x32_bf16 v[124:127], v[148:151], v[164:167], v[124:127]
	v_mfma_f32_16x16x32_bf16 v[120:123], v[156:159], v[164:167], v[120:123]
	v_mfma_f32_16x16x32_bf16 v[112:115], v[148:151], v[172:175], v[112:115]
	v_mfma_f32_16x16x32_bf16 v[104:107], v[156:159], v[172:175], v[104:107]
	v_mfma_f32_16x16x32_bf16 v[96:99], v[148:151], v[180:183], v[96:99]
	v_mfma_f32_16x16x32_bf16 v[88:91], v[156:159], v[180:183], v[88:91]
	v_mfma_f32_16x16x32_bf16 v[80:83], v[148:151], v[188:191], v[80:83]
	v_mfma_f32_16x16x32_bf16 v[72:75], v[156:159], v[188:191], v[72:75]
	s_setprio 0
	s_barrier
	s_add_i32 s10, s18, s95
	s_mov_b32 m0, s10
	ds_read_b128 v[160:163], v245 offset:16384
	ds_read_b128 v[164:167], v245 offset:17408
	ds_read_b128 v[168:171], v245 offset:18432
	ds_read_b128 v[172:175], v245 offset:19456
	ds_read_b128 v[176:179], v245 offset:20480
	ds_read_b128 v[180:183], v245 offset:21504
	ds_read_b128 v[184:187], v245 offset:22528
	ds_read_b128 v[188:191], v245 offset:23552
	global_load_lds_dwordx4 v218, s[48:49]
	s_add_i32 m0, s10, 0x2000
	s_add_u32 s10, s48, 0xb0000
	s_addc_u32 s11, s49, 0
	s_add_i32 s18, s19, s95
	global_load_lds_dwordx4 v222, s[48:49]
	s_mov_b32 m0, s18
	s_nop 0
	global_load_lds_dwordx4 v218, s[10:11]
	s_add_i32 m0, s18, 0x2000
	s_nop 0
	global_load_lds_dwordx4 v222, s[10:11]
	s_mov_b32 m0, s33
	s_nop 0
	global_load_lds_dwordx4 v216, s[50:51]
	s_mov_b32 m0, s82
	s_nop 0
	global_load_lds_dwordx4 v220, s[50:51]
	s_waitcnt vmcnt(8)
	s_waitcnt lgkmcnt(0)
	s_barrier
	s_setprio 1
	v_mfma_f32_16x16x32_bf16 v[60:63], v[64:67], v[160:163], v[60:63]
	v_mfma_f32_16x16x32_bf16 v[52:55], v[136:139], v[160:163], v[52:55]
	v_mfma_f32_16x16x32_bf16 v[44:47], v[64:67], v[168:171], v[44:47]
	v_mfma_f32_16x16x32_bf16 v[36:39], v[136:139], v[168:171], v[36:39]
	v_mfma_f32_16x16x32_bf16 v[28:31], v[64:67], v[176:179], v[28:31]
	v_mfma_f32_16x16x32_bf16 v[20:23], v[136:139], v[176:179], v[20:23]
	v_mfma_f32_16x16x32_bf16 v[12:15], v[64:67], v[184:187], v[12:15]
	v_mfma_f32_16x16x32_bf16 v[4:7], v[136:139], v[184:187], v[4:7]
	v_mfma_f32_16x16x32_bf16 v[60:63], v[68:71], v[164:167], v[60:63]
	v_mfma_f32_16x16x32_bf16 v[52:55], v[140:143], v[164:167], v[52:55]
	v_mfma_f32_16x16x32_bf16 v[44:47], v[68:71], v[172:175], v[44:47]
	v_mfma_f32_16x16x32_bf16 v[36:39], v[140:143], v[172:175], v[36:39]
	v_mfma_f32_16x16x32_bf16 v[28:31], v[68:71], v[180:183], v[28:31]
	v_mfma_f32_16x16x32_bf16 v[20:23], v[140:143], v[180:183], v[20:23]
	v_mfma_f32_16x16x32_bf16 v[12:15], v[68:71], v[188:191], v[12:15]
	v_mfma_f32_16x16x32_bf16 v[4:7], v[140:143], v[188:191], v[4:7]
	v_mfma_f32_16x16x32_bf16 v[56:59], v[144:147], v[160:163], v[56:59]
	v_mfma_f32_16x16x32_bf16 v[48:51], v[152:155], v[160:163], v[48:51]
	v_mfma_f32_16x16x32_bf16 v[40:43], v[144:147], v[168:171], v[40:43]
	v_mfma_f32_16x16x32_bf16 v[32:35], v[152:155], v[168:171], v[32:35]
	v_mfma_f32_16x16x32_bf16 v[24:27], v[144:147], v[176:179], v[24:27]
	v_mfma_f32_16x16x32_bf16 v[16:19], v[152:155], v[176:179], v[16:19]
	v_mfma_f32_16x16x32_bf16 v[8:11], v[144:147], v[184:187], v[8:11]
	v_mfma_f32_16x16x32_bf16 v[0:3], v[152:155], v[184:187], v[0:3]
	v_mfma_f32_16x16x32_bf16 v[56:59], v[148:151], v[164:167], v[56:59]
	v_mfma_f32_16x16x32_bf16 v[48:51], v[156:159], v[164:167], v[48:51]
	v_mfma_f32_16x16x32_bf16 v[40:43], v[148:151], v[172:175], v[40:43]
	v_mfma_f32_16x16x32_bf16 v[32:35], v[156:159], v[172:175], v[32:35]
	v_mfma_f32_16x16x32_bf16 v[24:27], v[148:151], v[180:183], v[24:27]
	v_mfma_f32_16x16x32_bf16 v[16:19], v[156:159], v[180:183], v[16:19]
	v_mfma_f32_16x16x32_bf16 v[8:11], v[148:151], v[188:191], v[8:11]
	v_mfma_f32_16x16x32_bf16 v[0:3], v[156:159], v[188:191], v[0:3]
	s_setprio 0
	s_barrier
; #define PG8_STAGE(bufoff, gbase, voff) do { _Pragma("unroll") for (int _i = 0; _i < 2; ++_i) \
;         __builtin_amdgcn_global_load_lds((const unsigned*)((const char*)(gbase) + (voff)[_i]), (PG8_LAS unsigned*)(lds + (bufoff) + ldsw + _i * 8192), 16, 0, 0); } while (0)
; #define PG8_BAR __builtin_amdgcn_s_barrier()
; template <class Epi, class Sched, bool ALIGN_EPI = false, bool SP2 = false>
; __device__ __forceinline__ void gemm_phase(PG8_LAS unsigned char* lds, const Gemm g, const Sched& S, const Epi& E, const int wave0) {
;     ...
;             PG8_LDB(B0, 1, 0); PG8_LDB(B1, 1, 1); PG8_SCHED; PG8_LDA(At, 1, 0); PG8_STAGE(PG8_SA(0, 1), a2 + hstep, voffA);
;             PG8_WAIT_V(8); PG8_WAIT_L(0); PG8_BAR; PG8_MMA(0, 0, At, B0); PG8_MMA(0, 1, At, B1); PG8_BAR; PG8_SCHED;
;             PG8_LDA(At, 1, 1); PG8_STAGE(PG8_SB(1, 0), b3, voffB); PG8_STAGE(PG8_SB(1, 1), b3 + hstep, voffB); PG8_STAGE(PG8_SA(1, 0), a3, voffA);
;             PG8_WAIT_V(8); PG8_WAIT_L(0); PG8_BAR; PG8_MMA(1, 0, At, B0); PG8_MMA(1, 1, At, B1); PG8_BAR; PG8_SCHED;
;             } else {
;             PG8_LDB(B0, 0, 0); PG8_SCHED; PG8_LDA(At, 0, 0); PG8_STAGE(PG8_SA(1, 1), a1 + hstep, voffA);
;             PG8_WAIT_L(8); PG8_BAR; PG8_WAIT_L(0); PG8_MMA(0, 0, At, B0); PG8_BAR; PG8_SCHED;
;             PG8_LDB(B1, 0, 1); PG8_STAGE(PG8_SB(0, 0), b2, voffB);
;             PG8_BAR; PG8_WAIT_L(0); PG8_MMA(0, 1, At, B1); PG8_BAR;
;             PG8_LDA(At, 0, 1); PG8_STAGE(PG8_SA(0, 0), a2, voffA);
;             PG8_BAR; PG8_WAIT_L(0); PG8_MMA(1, 0, At, B0); PG8_BAR; PG8_SCHED;
;             PG8_STAGE(PG8_SB(0, 1), b2 + hstep, voffB);
;             PG8_WAIT_V(6); PG8_BAR; PG8_MMA(1, 1, At, B1); PG8_BAR;
;             PG8_LDB(B0, 1, 0); PG8_SCHED; PG8_LDA(At, 1, 0); PG8_STAGE(PG8_SA(0, 1), a2 + hstep, voffA);
;             PG8_WAIT_L(8); PG8_BAR; PG8_WAIT_L(0); PG8_MMA(0, 0, At, B0); PG8_BAR; PG8_SCHED;
;             PG8_LDB(B1, 1, 1); PG8_STAGE(PG8_SB(1, 0), b3, voffB);
;             PG8_BAR; PG8_WAIT_L(0); PG8_MMA(0, 1, At, B1); PG8_BAR;
;             PG8_LDA(At, 1, 1); PG8_STAGE(PG8_SA(1, 0), a3, voffA);
;             PG8_BAR; PG8_WAIT_L(0); PG8_MMA(1, 0, At, B0); PG8_BAR; PG8_SCHED;
;             PG8_STAGE(PG8_SB(1, 1), b3 + hstep, voffB);
;             PG8_WAIT_V(6); PG8_BAR; PG8_MMA(1, 1, At, B1); PG8_BAR;
;             }
;         }
;         if constexpr (ALIGN_EPI) { if (wr == 0) PG8_BAR; }
	s_add_i32 s18, 0, 0x18000
	s_add_i32 s19, 0, 0x1c000
	v_add_u32_e32 v140, s18, v247
	v_add_u32_e32 v156, s19, v247
	ds_read_b128 v[64:67], v140
	ds_read_b128 v[68:71], v140 offset:1024
	ds_read_b128 v[136:139], v140 offset:2048
	ds_read_b128 v[140:143], v140 offset:3072
	ds_read_b128 v[144:147], v156
	ds_read_b128 v[148:151], v156 offset:1024
	ds_read_b128 v[152:155], v156 offset:2048
	ds_read_b128 v[156:159], v156 offset:3072
	s_add_u32 s10, s50, 0xb0000
	s_addc_u32 s11, s51, 0
	s_mov_b32 m0, s16
	ds_read_b128 v[160:163], v245 offset:32768
	ds_read_b128 v[164:167], v245 offset:33792
	ds_read_b128 v[168:171], v245 offset:34816
	ds_read_b128 v[172:175], v245 offset:35840
	ds_read_b128 v[176:179], v245 offset:36864
	ds_read_b128 v[180:183], v245 offset:37888
	ds_read_b128 v[184:187], v245 offset:38912
	ds_read_b128 v[188:191], v245 offset:39936
	global_load_lds_dwordx4 v216, s[10:11]
	s_mov_b32 m0, s83
	s_nop 0
	global_load_lds_dwordx4 v220, s[10:11]
	s_waitcnt vmcnt(8)
	s_waitcnt lgkmcnt(0)
	s_barrier
	s_setprio 1
	v_mfma_f32_16x16x32_bf16 v[132:135], v[64:67], v[160:163], v[132:135]
	v_mfma_f32_16x16x32_bf16 v[128:131], v[136:139], v[160:163], v[128:131]
	v_mfma_f32_16x16x32_bf16 v[116:119], v[64:67], v[168:171], v[116:119]
	v_mfma_f32_16x16x32_bf16 v[108:111], v[136:139], v[168:171], v[108:111]
	v_mfma_f32_16x16x32_bf16 v[100:103], v[64:67], v[176:179], v[100:103]
	v_mfma_f32_16x16x32_bf16 v[92:95], v[136:139], v[176:179], v[92:95]
	v_mfma_f32_16x16x32_bf16 v[84:87], v[64:67], v[184:187], v[84:87]
	v_mfma_f32_16x16x32_bf16 v[76:79], v[136:139], v[184:187], v[76:79]
	v_mfma_f32_16x16x32_bf16 v[132:135], v[68:71], v[164:167], v[132:135]
	v_mfma_f32_16x16x32_bf16 v[128:131], v[140:143], v[164:167], v[128:131]
	v_mfma_f32_16x16x32_bf16 v[116:119], v[68:71], v[172:175], v[116:119]
	v_mfma_f32_16x16x32_bf16 v[108:111], v[140:143], v[172:175], v[108:111]
	v_mfma_f32_16x16x32_bf16 v[100:103], v[68:71], v[180:183], v[100:103]
	v_mfma_f32_16x16x32_bf16 v[92:95], v[140:143], v[180:183], v[92:95]
	v_mfma_f32_16x16x32_bf16 v[84:87], v[68:71], v[188:191], v[84:87]
	v_mfma_f32_16x16x32_bf16 v[76:79], v[140:143], v[188:191], v[76:79]
	v_mfma_f32_16x16x32_bf16 v[124:127], v[144:147], v[160:163], v[124:127]
	v_mfma_f32_16x16x32_bf16 v[120:123], v[152:155], v[160:163], v[120:123]
	v_mfma_f32_16x16x32_bf16 v[112:115], v[144:147], v[168:171], v[112:115]
	v_mfma_f32_16x16x32_bf16 v[104:107], v[152:155], v[168:171], v[104:107]
	v_mfma_f32_16x16x32_bf16 v[96:99], v[144:147], v[176:179], v[96:99]
	v_mfma_f32_16x16x32_bf16 v[88:91], v[152:155], v[176:179], v[88:91]
	v_mfma_f32_16x16x32_bf16 v[80:83], v[144:147], v[184:187], v[80:83]
	v_mfma_f32_16x16x32_bf16 v[72:75], v[152:155], v[184:187], v[72:75]
	v_mfma_f32_16x16x32_bf16 v[124:127], v[148:151], v[164:167], v[124:127]
	v_mfma_f32_16x16x32_bf16 v[120:123], v[156:159], v[164:167], v[120:123]
	v_mfma_f32_16x16x32_bf16 v[112:115], v[148:151], v[172:175], v[112:115]
	v_mfma_f32_16x16x32_bf16 v[104:107], v[156:159], v[172:175], v[104:107]
	v_mfma_f32_16x16x32_bf16 v[96:99], v[148:151], v[180:183], v[96:99]
	v_mfma_f32_16x16x32_bf16 v[88:91], v[156:159], v[180:183], v[88:91]
	v_mfma_f32_16x16x32_bf16 v[80:83], v[148:151], v[188:191], v[80:83]
	v_mfma_f32_16x16x32_bf16 v[72:75], v[156:159], v[188:191], v[72:75]
	s_setprio 0
	s_barrier
	s_add_i32 s10, s18, s95
	s_add_i32 m0, s10, 0xffffff80
	ds_read_b128 v[160:163], v245 offset:49152
	ds_read_b128 v[164:167], v245 offset:50176
	ds_read_b128 v[168:171], v245 offset:51200
	ds_read_b128 v[172:175], v245 offset:52224
	ds_read_b128 v[176:179], v245 offset:53248
	ds_read_b128 v[180:183], v245 offset:54272
	ds_read_b128 v[184:187], v245 offset:55296
	ds_read_b128 v[188:191], v245 offset:56320
	global_load_lds_dwordx4 v218, s[48:49] offset:128
	s_add_i32 m0, s10, 0x1f80
	s_add_u32 s10, s48, 0xb0080
	s_addc_u32 s11, s49, 0
	s_add_i32 s18, s19, s95
	global_load_lds_dwordx4 v222, s[48:49] offset:128
	s_mov_b32 m0, s18
	s_nop 0
	global_load_lds_dwordx4 v218, s[10:11]
	s_add_i32 m0, s18, 0x2000
	s_nop 0
	global_load_lds_dwordx4 v222, s[10:11]
	s_add_i32 m0, s17, 0xffffff80
	s_nop 0
	global_load_lds_dwordx4 v216, s[50:51] offset:128
	s_add_i32 m0, s23, 0xffffff80
	s_nop 0
	global_load_lds_dwordx4 v220, s[50:51] offset:128
	s_waitcnt vmcnt(8)
	s_waitcnt lgkmcnt(0)
	s_barrier
	s_setprio 1
	v_mfma_f32_16x16x32_bf16 v[60:63], v[64:67], v[160:163], v[60:63]
	v_mfma_f32_16x16x32_bf16 v[52:55], v[136:139], v[160:163], v[52:55]
	v_mfma_f32_16x16x32_bf16 v[44:47], v[64:67], v[168:171], v[44:47]
	v_mfma_f32_16x16x32_bf16 v[36:39], v[136:139], v[168:171], v[36:39]
	v_mfma_f32_16x16x32_bf16 v[28:31], v[64:67], v[176:179], v[28:31]
	v_mfma_f32_16x16x32_bf16 v[20:23], v[136:139], v[176:179], v[20:23]
	v_mfma_f32_16x16x32_bf16 v[12:15], v[64:67], v[184:187], v[12:15]
	v_mfma_f32_16x16x32_bf16 v[4:7], v[136:139], v[184:187], v[4:7]
	v_mfma_f32_16x16x32_bf16 v[60:63], v[68:71], v[164:167], v[60:63]
	v_mfma_f32_16x16x32_bf16 v[52:55], v[140:143], v[164:167], v[52:55]
	v_mfma_f32_16x16x32_bf16 v[44:47], v[68:71], v[172:175], v[44:47]
	v_mfma_f32_16x16x32_bf16 v[36:39], v[140:143], v[172:175], v[36:39]
	v_mfma_f32_16x16x32_bf16 v[28:31], v[68:71], v[180:183], v[28:31]
	v_mfma_f32_16x16x32_bf16 v[20:23], v[140:143], v[180:183], v[20:23]
	v_mfma_f32_16x16x32_bf16 v[12:15], v[68:71], v[188:191], v[12:15]
	v_mfma_f32_16x16x32_bf16 v[4:7], v[140:143], v[188:191], v[4:7]
	v_mfma_f32_16x16x32_bf16 v[56:59], v[144:147], v[160:163], v[56:59]
	v_mfma_f32_16x16x32_bf16 v[48:51], v[152:155], v[160:163], v[48:51]
	v_mfma_f32_16x16x32_bf16 v[40:43], v[144:147], v[168:171], v[40:43]
	v_mfma_f32_16x16x32_bf16 v[32:35], v[152:155], v[168:171], v[32:35]
	v_mfma_f32_16x16x32_bf16 v[24:27], v[144:147], v[176:179], v[24:27]
	v_mfma_f32_16x16x32_bf16 v[16:19], v[152:155], v[176:179], v[16:19]
	v_mfma_f32_16x16x32_bf16 v[8:11], v[144:147], v[184:187], v[8:11]
	v_mfma_f32_16x16x32_bf16 v[0:3], v[152:155], v[184:187], v[0:3]
	v_mfma_f32_16x16x32_bf16 v[56:59], v[148:151], v[164:167], v[56:59]
	v_mfma_f32_16x16x32_bf16 v[48:51], v[156:159], v[164:167], v[48:51]
	v_mfma_f32_16x16x32_bf16 v[40:43], v[148:151], v[172:175], v[40:43]
	v_mfma_f32_16x16x32_bf16 v[32:35], v[156:159], v[172:175], v[32:35]
	v_mfma_f32_16x16x32_bf16 v[24:27], v[148:151], v[180:183], v[24:27]
	v_mfma_f32_16x16x32_bf16 v[16:19], v[156:159], v[180:183], v[16:19]
	v_mfma_f32_16x16x32_bf16 v[8:11], v[148:151], v[188:191], v[8:11]
	v_mfma_f32_16x16x32_bf16 v[0:3], v[156:159], v[188:191], v[0:3]
	s_setprio 0
	s_barrier
	s_add_i32 s59, s59, 2
	s_add_u32 s57, s57, 0x100
	s_addc_u32 s58, s58, 0
	s_cmp_gt_u32 s59, 41
	s_mov_b64 s[10:11], s[8:9]
	s_cbranch_scc0 .LBB0_1024
	s_and_b64 vcc, exec, s[66:67]
	s_cbranch_vccz .LBB0_1027
	s_barrier

; #define PG8_STAGE(bufoff, gbase, voff) do { _Pragma("unroll") for (int _i = 0; _i < 2; ++_i) \
;         __builtin_amdgcn_global_load_lds((const unsigned*)((const char*)(gbase) + (voff)[_i]), (PG8_LAS unsigned*)(lds + (bufoff) + ldsw + _i * 8192), 16, 0, 0); } while (0)
; #define PG8_LDA(dst, b, h) do { _Pragma("unroll") for (int m = 0; m < 4; ++m) _Pragma("unroll") for (int k = 0; k < 2; ++k) dst[m][k] = *(const PG8_LAS bf16x8*)(lds + PG8_SA(b, h) + aoff + m * 2048 + k * 1024); } while (0)
; #define PG8_LDB(dst, b, h) do { _Pragma("unroll") for (int n = 0; n < 2; ++n) _Pragma("unroll") for (int k = 0; k < 2; ++k) dst[n][k] = *(const PG8_LAS bf16x8*)(lds + PG8_SB(b, h) + boff + n * 2048 + k * 1024); } while (0)
; #define PG8_WAIT_V(n) asm volatile("s_waitcnt vmcnt(" #n ")" ::: "memory")
; #define PG8_WAIT_L(n) asm volatile("s_waitcnt lgkmcnt(" #n ")" ::: "memory")
; #define PG8_BAR __builtin_amdgcn_s_barrier()
; #define PG8_SCHED __builtin_amdgcn_sched_barrier(0)
; template <class Epi, class Sched, bool ALIGN_EPI = false, bool SP2 = false>
; __device__ __forceinline__ void gemm_phase(PG8_LAS unsigned char* lds, const Gemm g, const Sched& S, const Epi& E, const int wave0) {
;     ...
;         const char* nA = has_next ? (const char*)g.A + (size_t)nxt.pm * tstep : cA; const char* nB = has_next ? (const char*)g.Bt + (size_t)nxt.pn * tstep : cB;
;         for (int t = 0; t < nt; t += 2) {
;             const bool last = (t == nt - 2);
;             const char* a1 = cA + (size_t)(t + 1) * kstep;
;             const char* a2 = last ? nA : cA + (size_t)(t + 2) * kstep; const char* b2 = last ? nB : cB + (size_t)(t + 2) * kstep;
;             const char* a3 = a2 + kstep; const char* b3 = b2 + kstep;
;             if (last && has_next) S.a_ready(nxt);
;             if constexpr (SP2) {
;             PG8_LDB(B0, 0, 0); PG8_LDB(B1, 0, 1); PG8_SCHED; PG8_LDA(At, 0, 0); PG8_STAGE(PG8_SA(1, 1), a1 + hstep, voffA);
;             PG8_WAIT_V(8); PG8_WAIT_L(0); PG8_BAR; PG8_MMA(0, 0, At, B0); PG8_MMA(0, 1, At, B1); PG8_BAR; PG8_SCHED;
;             PG8_LDA(At, 0, 1); PG8_STAGE(PG8_SB(0, 0), b2, voffB); PG8_STAGE(PG8_SB(0, 1), b2 + hstep, voffB); PG8_STAGE(PG8_SA(0, 0), a2, voffA);
;             PG8_WAIT_V(8); PG8_WAIT_L(0); PG8_BAR; PG8_MMA(1, 0, At, B0); PG8_MMA(1, 1, At, B1); PG8_BAR; PG8_SCHED;
.LBB0_1140:
	s_add_u32 s18, s10, 0xfffc0080
	s_addc_u32 s19, s11, -1
	s_add_i32 s64, 0, 0x10000
	s_cmp_eq_u32 s63, 12
	s_cselect_b32 s59, s9, s19
	s_cselect_b32 s58, s49, s18
	s_cselect_b32 s57, s47, s62
	s_cselect_b32 s56, s60, s61
	s_add_i32 s65, 0, 0x14000
	v_add_u32_e32 v140, s64, v247
	v_add_u32_e32 v156, s65, v247
	ds_read_b128 v[64:67], v140
	ds_read_b128 v[68:71], v140 offset:1024
	ds_read_b128 v[136:139], v140 offset:2048
	ds_read_b128 v[140:143], v140 offset:3072
	ds_read_b128 v[144:147], v156
	ds_read_b128 v[148:151], v156 offset:1024
	ds_read_b128 v[152:155], v156 offset:2048
	ds_read_b128 v[156:159], v156 offset:3072
	s_add_i32 m0, s33, 0xc000
	ds_read_b128 v[160:163], v245
	ds_read_b128 v[164:167], v245 offset:1024
	ds_read_b128 v[168:171], v245 offset:2048
	ds_read_b128 v[172:175], v245 offset:3072
	ds_read_b128 v[176:179], v245 offset:4096
	ds_read_b128 v[180:183], v245 offset:5120
	ds_read_b128 v[184:187], v245 offset:6144
	ds_read_b128 v[188:191], v245 offset:7168
	global_load_lds_dwordx4 v224, s[10:11]
	s_add_i32 m0, s33, 0xe000
	s_nop 0
	global_load_lds_dwordx4 v226, s[10:11]
	s_waitcnt vmcnt(8)
	s_waitcnt lgkmcnt(0)
	s_barrier
	s_setprio 1
	v_mfma_f32_16x16x32_bf16 v[132:135], v[64:67], v[160:163], v[132:135]
	v_mfma_f32_16x16x32_bf16 v[128:131], v[136:139], v[160:163], v[128:131]
	v_mfma_f32_16x16x32_bf16 v[116:119], v[64:67], v[168:171], v[116:119]
	v_mfma_f32_16x16x32_bf16 v[108:111], v[136:139], v[168:171], v[108:111]
	v_mfma_f32_16x16x32_bf16 v[100:103], v[64:67], v[176:179], v[100:103]
	v_mfma_f32_16x16x32_bf16 v[92:95], v[136:139], v[176:179], v[92:95]
	v_mfma_f32_16x16x32_bf16 v[84:87], v[64:67], v[184:187], v[84:87]
	v_mfma_f32_16x16x32_bf16 v[76:79], v[136:139], v[184:187], v[76:79]
	v_mfma_f32_16x16x32_bf16 v[132:135], v[68:71], v[164:167], v[132:135]
	v_mfma_f32_16x16x32_bf16 v[128:131], v[140:143], v[164:167], v[128:131]
	v_mfma_f32_16x16x32_bf16 v[116:119], v[68:71], v[172:175], v[116:119]
	v_mfma_f32_16x16x32_bf16 v[108:111], v[140:143], v[172:175], v[108:111]
	v_mfma_f32_16x16x32_bf16 v[100:103], v[68:71], v[180:183], v[100:103]
	v_mfma_f32_16x16x32_bf16 v[92:95], v[140:143], v[180:183], v[92:95]
	v_mfma_f32_16x16x32_bf16 v[84:87], v[68:71], v[188:191], v[84:87]
	v_mfma_f32_16x16x32_bf16 v[76:79], v[140:143], v[188:191], v[76:79]
	v_mfma_f32_16x16x32_bf16 v[124:127], v[144:147], v[160:163], v[124:127]
	v_mfma_f32_16x16x32_bf16 v[120:123], v[152:155], v[160:163], v[120:123]
	v_mfma_f32_16x16x32_bf16 v[112:115], v[144:147], v[168:171], v[112:115]
	v_mfma_f32_16x16x32_bf16 v[104:107], v[152:155], v[168:171], v[104:107]
	v_mfma_f32_16x16x32_bf16 v[96:99], v[144:147], v[176:179], v[96:99]
	v_mfma_f32_16x16x32_bf16 v[88:91], v[152:155], v[176:179], v[88:91]
	v_mfma_f32_16x16x32_bf16 v[80:83], v[144:147], v[184:187], v[80:83]
	v_mfma_f32_16x16x32_bf16 v[72:75], v[152:155], v[184:187], v[72:75]
	v_mfma_f32_16x16x32_bf16 v[124:127], v[148:151], v[164:167], v[124:127]
	v_mfma_f32_16x16x32_bf16 v[120:123], v[156:159], v[164:167], v[120:123]
	v_mfma_f32_16x16x32_bf16 v[112:115], v[148:151], v[172:175], v[112:115]
	v_mfma_f32_16x16x32_bf16 v[104:107], v[156:159], v[172:175], v[104:107]
	v_mfma_f32_16x16x32_bf16 v[96:99], v[148:151], v[180:183], v[96:99]
	v_mfma_f32_16x16x32_bf16 v[88:91], v[156:159], v[180:183], v[88:91]
	v_mfma_f32_16x16x32_bf16 v[80:83], v[148:151], v[188:191], v[80:83]
	v_mfma_f32_16x16x32_bf16 v[72:75], v[156:159], v[188:191], v[72:75]
	s_setprio 0
	s_barrier
	s_add_i32 s18, s64, s95
	s_mov_b32 m0, s18
	ds_read_b128 v[160:163], v245 offset:16384
	ds_read_b128 v[164:167], v245 offset:17408
	ds_read_b128 v[168:171], v245 offset:18432
	ds_read_b128 v[172:175], v245 offset:19456
	ds_read_b128 v[176:179], v245 offset:20480
	ds_read_b128 v[180:183], v245 offset:21504
	ds_read_b128 v[184:187], v245 offset:22528
	ds_read_b128 v[188:191], v245 offset:23552
	global_load_lds_dwordx4 v218, s[56:57]
	s_add_i32 m0, s18, 0x2000
	s_add_u32 s18, s56, 0x40000
	s_addc_u32 s19, s57, 0
	s_add_i32 s64, s65, s95
	global_load_lds_dwordx4 v222, s[56:57]
	s_mov_b32 m0, s64
	s_nop 0
	global_load_lds_dwordx4 v218, s[18:19]
	s_add_i32 m0, s64, 0x2000
	s_nop 0
	global_load_lds_dwordx4 v222, s[18:19]
	s_mov_b32 m0, s33
	s_nop 0
	global_load_lds_dwordx4 v216, s[58:59]
	s_mov_b32 m0, s82
	s_nop 0
	global_load_lds_dwordx4 v220, s[58:59]
	s_waitcnt vmcnt(8)
	s_waitcnt lgkmcnt(0)
	s_barrier
	s_setprio 1
	v_mfma_f32_16x16x32_bf16 v[60:63], v[64:67], v[160:163], v[60:63]
	v_mfma_f32_16x16x32_bf16 v[52:55], v[136:139], v[160:163], v[52:55]
	v_mfma_f32_16x16x32_bf16 v[44:47], v[64:67], v[168:171], v[44:47]
	v_mfma_f32_16x16x32_bf16 v[36:39], v[136:139], v[168:171], v[36:39]
	v_mfma_f32_16x16x32_bf16 v[28:31], v[64:67], v[176:179], v[28:31]
	v_mfma_f32_16x16x32_bf16 v[20:23], v[136:139], v[176:179], v[20:23]
	v_mfma_f32_16x16x32_bf16 v[12:15], v[64:67], v[184:187], v[12:15]
	v_mfma_f32_16x16x32_bf16 v[4:7], v[136:139], v[184:187], v[4:7]
	v_mfma_f32_16x16x32_bf16 v[60:63], v[68:71], v[164:167], v[60:63]
	v_mfma_f32_16x16x32_bf16 v[52:55], v[140:143], v[164:167], v[52:55]
	v_mfma_f32_16x16x32_bf16 v[44:47], v[68:71], v[172:175], v[44:47]
	v_mfma_f32_16x16x32_bf16 v[36:39], v[140:143], v[172:175], v[36:39]
	v_mfma_f32_16x16x32_bf16 v[28:31], v[68:71], v[180:183], v[28:31]
	v_mfma_f32_16x16x32_bf16 v[20:23], v[140:143], v[180:183], v[20:23]
	v_mfma_f32_16x16x32_bf16 v[12:15], v[68:71], v[188:191], v[12:15]
	v_mfma_f32_16x16x32_bf16 v[4:7], v[140:143], v[188:191], v[4:7]
	v_mfma_f32_16x16x32_bf16 v[56:59], v[144:147], v[160:163], v[56:59]
	v_mfma_f32_16x16x32_bf16 v[48:51], v[152:155], v[160:163], v[48:51]
	v_mfma_f32_16x16x32_bf16 v[40:43], v[144:147], v[168:171], v[40:43]
	v_mfma_f32_16x16x32_bf16 v[32:35], v[152:155], v[168:171], v[32:35]
	v_mfma_f32_16x16x32_bf16 v[24:27], v[144:147], v[176:179], v[24:27]
	v_mfma_f32_16x16x32_bf16 v[16:19], v[152:155], v[176:179], v[16:19]
	v_mfma_f32_16x16x32_bf16 v[8:11], v[144:147], v[184:187], v[8:11]
	v_mfma_f32_16x16x32_bf16 v[0:3], v[152:155], v[184:187], v[0:3]
	v_mfma_f32_16x16x32_bf16 v[56:59], v[148:151], v[164:167], v[56:59]
	v_mfma_f32_16x16x32_bf16 v[48:51], v[156:159], v[164:167], v[48:51]
	v_mfma_f32_16x16x32_bf16 v[40:43], v[148:151], v[172:175], v[40:43]
	v_mfma_f32_16x16x32_bf16 v[32:35], v[156:159], v[172:175], v[32:35]
	v_mfma_f32_16x16x32_bf16 v[24:27], v[148:151], v[180:183], v[24:27]
	v_mfma_f32_16x16x32_bf16 v[16:19], v[156:159], v[180:183], v[16:19]
	v_mfma_f32_16x16x32_bf16 v[8:11], v[148:151], v[188:191], v[8:11]
	v_mfma_f32_16x16x32_bf16 v[0:3], v[156:159], v[188:191], v[0:3]
	s_setprio 0
	s_barrier
; #define PG8_STAGE(bufoff, gbase, voff) do { _Pragma("unroll") for (int _i = 0; _i < 2; ++_i) \
;         __builtin_amdgcn_global_load_lds((const unsigned*)((const char*)(gbase) + (voff)[_i]), (PG8_LAS unsigned*)(lds + (bufoff) + ldsw + _i * 8192), 16, 0, 0); } while (0)
; #define PG8_BAR __builtin_amdgcn_s_barrier()
; template <class Epi, class Sched, bool ALIGN_EPI = false, bool SP2 = false>
; __device__ __forceinline__ void gemm_phase(PG8_LAS unsigned char* lds, const Gemm g, const Sched& S, const Epi& E, const int wave0) {
;     ...
;             PG8_LDB(B0, 1, 0); PG8_LDB(B1, 1, 1); PG8_SCHED; PG8_LDA(At, 1, 0); PG8_STAGE(PG8_SA(0, 1), a2 + hstep, voffA);
;             PG8_WAIT_V(8); PG8_WAIT_L(0); PG8_BAR; PG8_MMA(0, 0, At, B0); PG8_MMA(0, 1, At, B1); PG8_BAR; PG8_SCHED;
;             PG8_LDA(At, 1, 1); PG8_STAGE(PG8_SB(1, 0), b3, voffB); PG8_STAGE(PG8_SB(1, 1), b3 + hstep, voffB); PG8_STAGE(PG8_SA(1, 0), a3, voffA);
;             PG8_WAIT_V(8); PG8_WAIT_L(0); PG8_BAR; PG8_MMA(1, 0, At, B0); PG8_MMA(1, 1, At, B1); PG8_BAR; PG8_SCHED;
;             } else {
;             PG8_LDB(B0, 0, 0); PG8_SCHED; PG8_LDA(At, 0, 0); PG8_STAGE(PG8_SA(1, 1), a1 + hstep, voffA);
;             PG8_WAIT_L(8); PG8_BAR; PG8_WAIT_L(0); PG8_MMA(0, 0, At, B0); PG8_BAR; PG8_SCHED;
;             PG8_LDB(B1, 0, 1); PG8_STAGE(PG8_SB(0, 0), b2, voffB);
;             PG8_BAR; PG8_WAIT_L(0); PG8_MMA(0, 1, At, B1); PG8_BAR;
;             PG8_LDA(At, 0, 1); PG8_STAGE(PG8_SA(0, 0), a2, voffA);
;             PG8_BAR; PG8_WAIT_L(0); PG8_MMA(1, 0, At, B0); PG8_BAR; PG8_SCHED;
;             PG8_STAGE(PG8_SB(0, 1), b2 + hstep, voffB);
;             PG8_WAIT_V(6); PG8_BAR; PG8_MMA(1, 1, At, B1); PG8_BAR;
;             PG8_LDB(B0, 1, 0); PG8_SCHED; PG8_LDA(At, 1, 0); PG8_STAGE(PG8_SA(0, 1), a2 + hstep, voffA);
;             PG8_WAIT_L(8); PG8_BAR; PG8_WAIT_L(0); PG8_MMA(0, 0, At, B0); PG8_BAR; PG8_SCHED;
;             PG8_LDB(B1, 1, 1); PG8_STAGE(PG8_SB(1, 0), b3, voffB);
;             PG8_BAR; PG8_WAIT_L(0); PG8_MMA(0, 1, At, B1); PG8_BAR;
;             PG8_LDA(At, 1, 1); PG8_STAGE(PG8_SA(1, 0), a3, voffA);
;             PG8_BAR; PG8_WAIT_L(0); PG8_MMA(1, 0, At, B0); PG8_BAR; PG8_SCHED;
;             PG8_STAGE(PG8_SB(1, 1), b3 + hstep, voffB);
;             PG8_WAIT_V(6); PG8_BAR; PG8_MMA(1, 1, At, B1); PG8_BAR;
;             }
;         }
;         if constexpr (ALIGN_EPI) { if (wr == 0) PG8_BAR; }
	s_add_i32 s64, 0, 0x18000
	s_add_i32 s65, 0, 0x1c000
	v_add_u32_e32 v140, s64, v247
	v_add_u32_e32 v156, s65, v247
	ds_read_b128 v[64:67], v140
	ds_read_b128 v[68:71], v140 offset:1024
	ds_read_b128 v[136:139], v140 offset:2048
	ds_read_b128 v[140:143], v140 offset:3072
	ds_read_b128 v[144:147], v156
	ds_read_b128 v[148:151], v156 offset:1024
	ds_read_b128 v[152:155], v156 offset:2048
	ds_read_b128 v[156:159], v156 offset:3072
	s_add_u32 s18, s58, 0x40000
	s_addc_u32 s19, s59, 0
	s_mov_b32 m0, s16
	ds_read_b128 v[160:163], v245 offset:32768
	ds_read_b128 v[164:167], v245 offset:33792
	ds_read_b128 v[168:171], v245 offset:34816
	ds_read_b128 v[172:175], v245 offset:35840
	ds_read_b128 v[176:179], v245 offset:36864
	ds_read_b128 v[180:183], v245 offset:37888
	ds_read_b128 v[184:187], v245 offset:38912
	ds_read_b128 v[188:191], v245 offset:39936
	global_load_lds_dwordx4 v216, s[18:19]
	s_mov_b32 m0, s83
	s_nop 0
	global_load_lds_dwordx4 v220, s[18:19]
	s_waitcnt vmcnt(8)
	s_waitcnt lgkmcnt(0)
	s_barrier
	s_setprio 1
	v_mfma_f32_16x16x32_bf16 v[132:135], v[64:67], v[160:163], v[132:135]
	v_mfma_f32_16x16x32_bf16 v[128:131], v[136:139], v[160:163], v[128:131]
	v_mfma_f32_16x16x32_bf16 v[116:119], v[64:67], v[168:171], v[116:119]
	v_mfma_f32_16x16x32_bf16 v[108:111], v[136:139], v[168:171], v[108:111]
	v_mfma_f32_16x16x32_bf16 v[100:103], v[64:67], v[176:179], v[100:103]
	v_mfma_f32_16x16x32_bf16 v[92:95], v[136:139], v[176:179], v[92:95]
	v_mfma_f32_16x16x32_bf16 v[84:87], v[64:67], v[184:187], v[84:87]
	v_mfma_f32_16x16x32_bf16 v[76:79], v[136:139], v[184:187], v[76:79]
	v_mfma_f32_16x16x32_bf16 v[132:135], v[68:71], v[164:167], v[132:135]
	v_mfma_f32_16x16x32_bf16 v[128:131], v[140:143], v[164:167], v[128:131]
	v_mfma_f32_16x16x32_bf16 v[116:119], v[68:71], v[172:175], v[116:119]
	v_mfma_f32_16x16x32_bf16 v[108:111], v[140:143], v[172:175], v[108:111]
	v_mfma_f32_16x16x32_bf16 v[100:103], v[68:71], v[180:183], v[100:103]
	v_mfma_f32_16x16x32_bf16 v[92:95], v[140:143], v[180:183], v[92:95]
	v_mfma_f32_16x16x32_bf16 v[84:87], v[68:71], v[188:191], v[84:87]
	v_mfma_f32_16x16x32_bf16 v[76:79], v[140:143], v[188:191], v[76:79]
	v_mfma_f32_16x16x32_bf16 v[124:127], v[144:147], v[160:163], v[124:127]
	v_mfma_f32_16x16x32_bf16 v[120:123], v[152:155], v[160:163], v[120:123]
	v_mfma_f32_16x16x32_bf16 v[112:115], v[144:147], v[168:171], v[112:115]
	v_mfma_f32_16x16x32_bf16 v[104:107], v[152:155], v[168:171], v[104:107]
	v_mfma_f32_16x16x32_bf16 v[96:99], v[144:147], v[176:179], v[96:99]
	v_mfma_f32_16x16x32_bf16 v[88:91], v[152:155], v[176:179], v[88:91]
	v_mfma_f32_16x16x32_bf16 v[80:83], v[144:147], v[184:187], v[80:83]
	v_mfma_f32_16x16x32_bf16 v[72:75], v[152:155], v[184:187], v[72:75]
	v_mfma_f32_16x16x32_bf16 v[124:127], v[148:151], v[164:167], v[124:127]
	v_mfma_f32_16x16x32_bf16 v[120:123], v[156:159], v[164:167], v[120:123]
	v_mfma_f32_16x16x32_bf16 v[112:115], v[148:151], v[172:175], v[112:115]
	v_mfma_f32_16x16x32_bf16 v[104:107], v[156:159], v[172:175], v[104:107]
	v_mfma_f32_16x16x32_bf16 v[96:99], v[148:151], v[180:183], v[96:99]
	v_mfma_f32_16x16x32_bf16 v[88:91], v[156:159], v[180:183], v[88:91]
	v_mfma_f32_16x16x32_bf16 v[80:83], v[148:151], v[188:191], v[80:83]
	v_mfma_f32_16x16x32_bf16 v[72:75], v[156:159], v[188:191], v[72:75]
	s_setprio 0
	s_barrier
	s_add_i32 s18, s64, s95
	s_add_i32 m0, s18, 0xffffff80
	ds_read_b128 v[160:163], v245 offset:49152
	ds_read_b128 v[164:167], v245 offset:50176
	ds_read_b128 v[168:171], v245 offset:51200
	ds_read_b128 v[172:175], v245 offset:52224
	ds_read_b128 v[176:179], v245 offset:53248
	ds_read_b128 v[180:183], v245 offset:54272
	ds_read_b128 v[184:187], v245 offset:55296
	ds_read_b128 v[188:191], v245 offset:56320
	global_load_lds_dwordx4 v218, s[56:57] offset:128
	s_add_i32 m0, s18, 0x1f80
	s_add_u32 s18, s56, 0x40080
	s_addc_u32 s19, s57, 0
	global_load_lds_dwordx4 v222, s[56:57] offset:128
	s_add_i32 s56, s65, s95
	s_mov_b32 m0, s56
	s_nop 0
	global_load_lds_dwordx4 v218, s[18:19]
	s_add_i32 m0, s56, 0x2000
	s_nop 0
	global_load_lds_dwordx4 v222, s[18:19]
	s_add_i32 m0, s17, 0xffffff80
	s_nop 0
	global_load_lds_dwordx4 v216, s[58:59] offset:128
	s_add_i32 m0, s23, 0xffffff80
	s_nop 0
	global_load_lds_dwordx4 v220, s[58:59] offset:128
	s_waitcnt vmcnt(8)
	s_waitcnt lgkmcnt(0)
	s_barrier
	s_setprio 1
	v_mfma_f32_16x16x32_bf16 v[60:63], v[64:67], v[160:163], v[60:63]
	v_mfma_f32_16x16x32_bf16 v[52:55], v[136:139], v[160:163], v[52:55]
	v_mfma_f32_16x16x32_bf16 v[44:47], v[64:67], v[168:171], v[44:47]
	v_mfma_f32_16x16x32_bf16 v[36:39], v[136:139], v[168:171], v[36:39]
	v_mfma_f32_16x16x32_bf16 v[28:31], v[64:67], v[176:179], v[28:31]
	v_mfma_f32_16x16x32_bf16 v[20:23], v[136:139], v[176:179], v[20:23]
	v_mfma_f32_16x16x32_bf16 v[12:15], v[64:67], v[184:187], v[12:15]
	v_mfma_f32_16x16x32_bf16 v[4:7], v[136:139], v[184:187], v[4:7]
	v_mfma_f32_16x16x32_bf16 v[60:63], v[68:71], v[164:167], v[60:63]
	v_mfma_f32_16x16x32_bf16 v[52:55], v[140:143], v[164:167], v[52:55]
	v_mfma_f32_16x16x32_bf16 v[44:47], v[68:71], v[172:175], v[44:47]
	v_mfma_f32_16x16x32_bf16 v[36:39], v[140:143], v[172:175], v[36:39]
	v_mfma_f32_16x16x32_bf16 v[28:31], v[68:71], v[180:183], v[28:31]
	v_mfma_f32_16x16x32_bf16 v[20:23], v[140:143], v[180:183], v[20:23]
	v_mfma_f32_16x16x32_bf16 v[12:15], v[68:71], v[188:191], v[12:15]
	v_mfma_f32_16x16x32_bf16 v[4:7], v[140:143], v[188:191], v[4:7]
	v_mfma_f32_16x16x32_bf16 v[56:59], v[144:147], v[160:163], v[56:59]
	v_mfma_f32_16x16x32_bf16 v[48:51], v[152:155], v[160:163], v[48:51]
	v_mfma_f32_16x16x32_bf16 v[40:43], v[144:147], v[168:171], v[40:43]
	v_mfma_f32_16x16x32_bf16 v[32:35], v[152:155], v[168:171], v[32:35]
	v_mfma_f32_16x16x32_bf16 v[24:27], v[144:147], v[176:179], v[24:27]
	v_mfma_f32_16x16x32_bf16 v[16:19], v[152:155], v[176:179], v[16:19]
	v_mfma_f32_16x16x32_bf16 v[8:11], v[144:147], v[184:187], v[8:11]
	v_mfma_f32_16x16x32_bf16 v[0:3], v[152:155], v[184:187], v[0:3]
	v_mfma_f32_16x16x32_bf16 v[56:59], v[148:151], v[164:167], v[56:59]
	v_mfma_f32_16x16x32_bf16 v[48:51], v[156:159], v[164:167], v[48:51]
	v_mfma_f32_16x16x32_bf16 v[40:43], v[148:151], v[172:175], v[40:43]
	v_mfma_f32_16x16x32_bf16 v[32:35], v[156:159], v[172:175], v[32:35]
	v_mfma_f32_16x16x32_bf16 v[24:27], v[148:151], v[180:183], v[24:27]
	v_mfma_f32_16x16x32_bf16 v[16:19], v[156:159], v[180:183], v[16:19]
	v_mfma_f32_16x16x32_bf16 v[8:11], v[148:151], v[188:191], v[8:11]
	v_mfma_f32_16x16x32_bf16 v[0:3], v[156:159], v[188:191], v[0:3]
	s_setprio 0
	s_barrier
	s_add_i32 s63, s63, 2
	s_add_u32 s10, s10, 0x100
	s_addc_u32 s11, s11, 0
	s_add_u32 s61, s61, 0x100
	s_addc_u32 s62, s62, 0
	s_cmp_gt_u32 s63, 13
	s_cbranch_scc0 .LBB0_1140
	s_and_b64 vcc, exec, s[66:67]
	s_cbranch_vccz .LBB0_1143
	s_barrier
